# P3: odd workgroups run the PLE-projection GEMM before the out-projection GEMM (desynchronises the two halves' memory-bound epilogues)
# speedup vs baseline: 1.0382x; 1.0024x over previous
; __global__ void __launch_bounds__(NTHREADS, 2) mk_fwd(Args a_unused_) {
;     ...
;         if (EN_P3 && lo <= pb + 4 && pb + 4 < hi_ph) { PH_PTRS
;             for (int r3_ = 0; r3_ < ((layer == 0) ? REP_P3 : 1); ++r3_) {
;             if (EN_P3A) { pg8::Gemm g{OATT, (const bf16*)(ws + (nsa ? WS_WNSA_OUT : WS_WMOBA_OUT)) + (size_t)j * D * D, M, D, D, D}; pg8::StaticOrder S; S.init(M, D, G, bx);
;               EpiRes E{layer == 0 ? a->x : nullptr, OG, (const bf16*)a->out, XBA, (bf16*)(ws + WS_XLOA), ssA};
.LBB0_1263:
	s_andn2_b64 vcc, exec, s[2:3]
	s_cbranch_vccnz .LBB0_1445
	s_mov_b32 s4, 0
	v_writelane_b32 v255, s4, 43
.Lp3_reenter:
	s_waitcnt lgkmcnt(0)
	v_readlane_b32 s4, v253, 2
	v_readlane_b32 s0, v253, 10
	v_readlane_b32 s5, v253, 3
	v_readlane_b32 s1, v253, 11
	s_load_dword s22, s[0:1], 0x0
	v_readlane_b32 s0, v254, 15
	v_readlane_b32 s2, v253, 0
	s_cmp_lg_u32 s0, 0
	s_mov_b64 s[20:21], 0
	s_waitcnt lgkmcnt(0)
	s_mov_b32 s23, s22
	v_readlane_b32 s3, v253, 1
	v_readlane_b32 s1, v254, 16
	s_cbranch_scc1 .LBB0_1266
	s_load_dwordx2 s[20:21], s[4:5], 0x0

; #define PG8_WAIT_V(n) asm volatile("s_waitcnt vmcnt(" #n ")" ::: "memory")
; #define PG8_BAR __builtin_amdgcn_s_barrier()
; template <class Epi, class Sched, bool ALIGN_EPI = false, bool SP2 = false>
; __device__ __forceinline__ void gemm_phase(PG8_LAS unsigned char* lds, const Gemm g, const Sched& S, const Epi& E, const int wv) {
;     ...
;     for (int i = 0; i < 2; ++i) { int R, C; stage_rc(tid * 16 + i * 8192, R, C); const int Rb = Epi::PERM ? ((R & ~31) + perm32(R & 31)) : R;
;         voffA[i] = (unsigned)(R * g.lda + C) * 2u; voffB[i] = (unsigned)(Rb * K + C) * 2u; }
;     const size_t kstep = (size_t)(BK * 2);
;     const size_t hstepB = (size_t)HALF * K * 2, hstepA = (size_t)HALF * g.lda * 2;
;     const size_t tstepA = 2 * hstepA, tstepB = 2 * hstepB;
;     const unsigned ldsw = (unsigned)wid * 1024u;
;     const int aoff = lds_byte(wr * 64 + fr, fq * 8), boff = lds_byte(wc * 32 + fr, fq * 8);
;     ...
;     Unit cur, nxt; int ui = 0;
;     if (!S.next(0, cur)) return;
;     f32x4 acc[2][2][4][2];
; #pragma unroll
;     for (int a = 0; a < 2; ++a)
; #pragma unroll
;         for (int b = 0; b < 2; ++b)
; #pragma unroll
;             for (int m = 0; m < 4; ++m)
; #pragma unroll
;                 for (int n = 0; n < 2; ++n) acc[a][b][m][n] = (f32x4){0.f, 0.f, 0.f, 0.f};
;     bf16x8 At[4][2], B0[2][2], B1[2][2];
;     const char* cA = (const char*)g.A + (size_t)cur.pm * tstepA; const char* cB = (const char*)g.Bt + (size_t)cur.pn * tstepB;
;     S.a_ready(cur);
;     if constexpr (SP2) {
;         PG8_STAGE(PG8_SB(0, 0), cB, voffB); PG8_STAGE(PG8_SB(0, 1), cB + hstepB, voffB); PG8_STAGE(PG8_SA(0, 0), cA, voffA); PG8_STAGE(PG8_SA(0, 1), cA + hstepA, voffA);
;         if (wr == 1) PG8_BAR;
;         PG8_WAIT_V(2); PG8_BAR;
;         PG8_STAGE(PG8_SB(1, 0), cB + kstep, voffB); PG8_STAGE(PG8_SA(1, 0), cA + kstep, voffA); PG8_STAGE(PG8_SB(1, 1), cB + hstepB + kstep, voffB);
;         PG8_WAIT_V(6); PG8_BAR;
; __global__ void __launch_bounds__(NTHREADS, 2) mk_fwd(Args a_unused_) {
;     ...
;             if (EN_P3A) { pg8::Gemm g{OATT, (const bf16*)(ws + (nsa ? WS_WNSA_OUT : WS_WMOBA_OUT)) + (size_t)j * D * D, M, D, D, D}; pg8::StaticOrder S; S.init(M, D, G, bx);
;               EpiRes E{layer == 0 ? a->x : nullptr, OG, (const bf16*)a->out, XBA, (bf16*)(ws + WS_XLOA), ssA};
;               pg8::gemm_phase<EpiRes, pg8::StaticOrder, true, true>(lds, g, S, E, wv); }
.LBB0_1268:
	v_cndmask_b32_e64 v1, 0, 1, s[8:9]
	v_cmp_ne_u32_e64 s[6:7], 1, v1
	s_andn2_b64 vcc, exec, s[8:9]
	s_ashr_i32 s27, s23, 31
	v_readlane_b32 s1, v255, 43
	s_cmp_eq_u32 s1, 0
	s_cbranch_scc0 .Lp3_noskip
	s_bitcmp1_b32 s2, 0
	s_cbranch_scc1 .LBB0_1376
.Lp3_noskip:
	s_cbranch_vccnz .LBB0_1376
	v_ashrrev_i32_e32 v2, 31, v0
	v_lshrrev_b32_e32 v2, 26, v2
	v_lshlrev_b32_e32 v1, 4, v0
	v_add_u32_e32 v2, v0, v2
	v_bfe_i32 v0, v0, 27, 1
	v_lshrrev_b32_e32 v0, 22, v0
	v_add_u32_e32 v0, v1, v0
	v_and_b32_e32 v0, 0xfffffc00, v0
	v_sub_u32_e32 v0, v1, v0
	v_ashrrev_i32_e32 v8, 6, v2
	v_lshrrev_b32_e32 v2, 4, v0
	v_bitop3_b32 v0, v2, v0, 32 bitop3:0x6c
	v_ashrrev_i32_e32 v3, 31, v0
	v_lshrrev_b32_e32 v3, 26, v3
	v_add_u32_e32 v3, v0, v3
	v_lshlrev_b32_e32 v2, 3, v8
	v_ashrrev_i32_e32 v9, 6, v3
	v_and_b32_e32 v3, 0xc0, v3
	v_and_b32_e32 v2, -16, v2
	v_sub_u32_e32 v0, v0, v3
	v_mov_b32_e32 v6, 1
	v_add_u32_e32 v2, v9, v2
	v_ashrrev_i16_sdwa v0, v6, sext(v0) dst_sel:DWORD dst_unused:UNUSED_PAD src0_sel:DWORD src1_sel:BYTE_0
	v_lshlrev_b32_e32 v4, 5, v8
	v_bfe_i32 v10, v0, 0, 16
	v_lshlrev_b32_e32 v0, 1, v2
	v_lshrrev_b32_e32 v3, 2, v2
	v_and_b32_e32 v5, 3, v9
	s_mov_b32 s5, 0x1fffe0
	v_and_b32_e32 v4, 32, v4
	v_and_b32_e32 v0, 24, v0
	v_and_b32_e32 v3, 4, v3
	v_and_or_b32 v5, v2, s5, v5
	v_or3_b32 v0, v5, v3, v0
	v_add_lshl_u32 v3, v4, v10, 1
	v_lshl_add_u32 v114, v0, 11, v3
	v_add_u32_e32 v0, 0x2000, v1
	v_ashrrev_i32_e32 v1, 31, v0
	v_lshrrev_b32_e32 v1, 22, v1
	v_add_u32_e32 v1, v0, v1
	v_ashrrev_i32_e32 v11, 10, v1
	v_mul_i32_i24_e32 v1, 0x400, v11
	v_sub_u32_e32 v0, v0, v1
	v_lshrrev_b32_e32 v1, 4, v0
	v_bitop3_b32 v0, v1, v0, 32 bitop3:0x6c
	v_lshl_add_u32 v112, v2, 11, v3
	v_ashrrev_i32_e32 v2, 31, v0
	s_ashr_i32 s1, s0, 6
	v_lshrrev_b32_e32 v2, 26, v2
	v_lshlrev_b32_e32 v1, 3, v11
	v_add_u32_e32 v2, v0, v2
	s_ashr_i32 s8, s0, 8
	s_lshl_b32 s36, s1, 10
	v_and_b32_e32 v1, -16, v1
	v_ashrrev_i32_e32 v12, 6, v2
	s_waitcnt lgkmcnt(0)
	s_add_u32 s37, s18, 0x1c000000
	v_readlane_b32 s10, v254, 17
	v_add_u32_e32 v1, v12, v1
	v_and_b32_e32 v4, 3, v12
	s_addc_u32 s62, s19, 0
	v_readlane_b32 s11, v254, 18
	v_and_or_b32 v4, v1, s5, v4
	s_and_b64 s[10:11], s[10:11], exec
	s_mov_b32 s5, 0x2b00000
	s_cselect_b32 s5, 0x1800000, s5
	s_add_u32 s5, s18, s5
	v_readlane_b32 s10, v254, 13
	s_addc_u32 s9, s19, 0
	s_lshl_b32 s10, s10, 21
	s_add_u32 s63, s5, s10
	v_and_b32_e32 v2, 0xc0, v2
	v_readlane_b32 s11, v254, 14
	s_addc_u32 s64, s9, 0
	s_ashr_i32 s5, s4, 31
	s_ashr_i32 s59, s58, 31
	v_sub_u32_e32 v0, v0, v2
	s_lshl_b64 s[10:11], s[4:5], 19
	s_lshl_b64 s[12:13], s[58:59], 19
	v_ashrrev_i16_sdwa v0, v6, sext(v0) dst_sel:DWORD dst_unused:UNUSED_PAD src0_sel:DWORD src1_sel:BYTE_0
	s_add_u32 s12, s63, s12
	v_lshlrev_b32_e32 v3, 5, v11
	v_bfe_i32 v13, v0, 0, 16
	v_lshlrev_b32_e32 v0, 1, v1
	v_lshrrev_b32_e32 v2, 2, v1
	s_addc_u32 s13, s64, s13
	s_add_i32 s65, s36, 0
	v_and_b32_e32 v3, 32, v3
	v_and_b32_e32 v0, 24, v0
	v_and_b32_e32 v2, 4, v2
	s_add_i32 m0, s65, 0x10000
	v_or3_b32 v0, v4, v2, v0
	v_add_lshl_u32 v2, v3, v13, 1
	global_load_lds_dwordx4 v114, s[12:13]
	s_add_i32 m0, s65, 0x12000
	v_lshl_add_u32 v142, v0, 11, v2
	s_add_u32 s30, s12, 0x40000
	global_load_lds_dwordx4 v142, s[12:13]
	s_addc_u32 s31, s13, 0
	s_add_i32 m0, s65, 0x14000
	v_lshl_add_u32 v140, v1, 11, v2
	global_load_lds_dwordx4 v114, s[30:31]
	s_add_i32 m0, s65, 0x16000
	s_add_u32 s10, s37, s10
	s_addc_u32 s11, s62, s11
	s_add_i32 s66, s65, 0x2000
	global_load_lds_dwordx4 v142, s[30:31]
	s_mov_b32 m0, s65
	s_add_u32 s30, s10, 0x40000
	global_load_lds_dwordx4 v112, s[10:11]
	s_mov_b32 m0, s66
	s_addc_u32 s31, s11, 0
	s_add_i32 s67, s65, 0x4000
	global_load_lds_dwordx4 v140, s[10:11]
	s_mov_b32 m0, s67
	s_add_i32 s68, s65, 0x6000
	global_load_lds_dwordx4 v112, s[30:31]
	s_mov_b32 m0, s68
	v_mov_b32_e32 v143, v115
	global_load_lds_dwordx4 v140, s[30:31]
	v_mov_b32_e32 v113, v115
	v_mov_b32_e32 v141, v115
	s_cmp_eq_u32 s8, 1
	v_mov_b32_e32 v252, 1
	v_lshl_add_u64 v[6:7], s[12:13], 0, v[114:115]
	v_lshl_add_u64 v[4:5], s[12:13], 0, v[142:143]
	v_lshl_add_u64 v[0:1], s[10:11], 0, v[112:113]
	s_cselect_b64 s[30:31], -1, 0
	s_cmp_lg_u32 s8, 1
	v_lshl_add_u64 v[2:3], s[10:11], 0, v[140:141]
	s_cbranch_scc1 .LBB0_1271
	s_barrier

; #define PG8_WAIT_V(n) asm volatile("s_waitcnt vmcnt(" #n ")" ::: "memory")
; #define PG8_BAR __builtin_amdgcn_s_barrier()
; template <class Epi, class Sched, bool ALIGN_EPI = false, bool SP2 = false>
; __device__ __forceinline__ void gemm_phase(PG8_LAS unsigned char* lds, const Gemm g, const Sched& S, const Epi& E, const int wv) {
;     ...
;     PG8_WAIT_V(0);
;     if constexpr (!ALIGN_EPI) { if (wr == 0) PG8_BAR; }
;     PG8_BAR;
.LBB0_1375:
	s_waitcnt vmcnt(0)
	s_barrier
	v_readlane_b32 s1, v255, 43
	s_cmp_eq_u32 s1, 1
	s_cbranch_scc1 .LBB0_1390

; __device__ __forceinline__ unsigned xb_add(unsigned* p, unsigned v) { return __hip_atomic_fetch_add(p, v, __ATOMIC_RELAXED, __HIP_MEMORY_SCOPE_AGENT); }
; __device__ __forceinline__ void xcd_barrier_complete(unsigned* bar, unsigned x, unsigned& nloc, unsigned& nx) {
;     const unsigned G = gridDim.x * gridDim.y * gridDim.z;
;     unsigned sum, cnt, mine, sp = 0u;
; __device__ __forceinline__ void xcd_barrier(const XcdBarrier& b) {
;     asm volatile("s_waitcnt vmcnt(0)" ::: "memory");
;     __syncthreads();
;     if (threadIdx.x == 0) {
;         unsigned* bar = b.bar;
;         __builtin_amdgcn_s_waitcnt(0);
;         unsigned nloc = b.st[0], nx = b.st[1];
;         if (nloc == 0u) { xcd_barrier_complete(bar, b.x, nloc, nx); b.st[0] = nloc; b.st[1] = nx; }
;         const unsigned old = xb_add(&bar[XB_XSUB(b.x)], 1u);
.LBB0_1389:
	s_barrier
	v_readlane_b32 s1, v255, 43
	s_cmp_eq_u32 s1, 0
	s_cbranch_scc0 .Lp3_done
	v_readlane_b32 s0, v253, 0
	s_bitcmp1_b32 s0, 0
	s_cbranch_scc0 .Lp3_done
	s_mov_b32 s1, 1
	v_writelane_b32 v255, s1, 43
	s_branch .Lp3_reenter
.Lp3_done:
.LBB0_1390:
	v_readlane_b32 s0, v254, 12
	s_add_i32 s0, s0, 6
	v_readlane_b32 s1, v253, 9
	s_cmp_ge_i32 s0, s1
	s_cbranch_scc1 .LBB0_1402
	s_waitcnt vmcnt(0)
	s_waitcnt vmcnt(0) lgkmcnt(0)
	s_barrier
	s_mov_b64 s[2:3], exec
	v_readlane_b32 s4, v253, 6
	v_readlane_b32 s5, v253, 7
	s_and_b64 s[4:5], s[2:3], s[4:5]
	s_movk_i32 s35, 0x3eff
	s_mov_b64 exec, s[4:5]
	s_cbranch_execz .LBB0_1444
	v_readlane_b32 s1, v254, 5
	s_waitcnt vmcnt(0) expcnt(0) lgkmcnt(0)
	s_nop 0
	v_mov_b32_e32 v0, s1
	ds_read_b32 v2, v0
	v_readlane_b32 s1, v254, 6
	s_waitcnt lgkmcnt(0)
	v_cmp_ne_u32_e32 vcc, 0, v2
	v_mov_b32_e32 v0, s1
	ds_read_b32 v0, v0
	s_cbranch_vccnz .LBB0_1408
	v_readlane_b32 s6, v253, 10
	v_readlane_b32 s7, v253, 11
	s_load_dwordx2 s[4:5], s[6:7], 0x4
	s_mov_b32 s10, 1
	s_waitcnt lgkmcnt(0)
	s_mul_i32 s1, s4, s22
	s_mul_i32 s1, s1, s5
	s_branch .LBB0_1395
